# stack14 + softmax temporaries renamed so P fragments are packed and written to LDS as soon as their exponentials exist (no LDS write latency at the step tail)
# baseline (speedup 1.0000x reference)
.Li0_sm:
	ds_read_b64_tr_b16 v[188:189], v158 offset:0x400
	ds_read_b64_tr_b16 v[190:191], v158 offset:0xc00
	ds_read_b64_tr_b16 v[192:193], v158 offset:0x600
	ds_read_b64_tr_b16 v[194:195], v158 offset:0xe00
	s_waitcnt lgkmcnt(6)
	v_mfma_f32_32x32x16_bf16 v[48:63], v[176:179], v[180:183], v[48:63]
	ds_read_b64_tr_b16 v[180:181], v158 offset:0x1000
	ds_read_b64_tr_b16 v[182:183], v158 offset:0x1800
	v_mul_f32_e32 v230, 0xbe0293ee, v166
	v_max_f32_e32 v228, v65, v65
	v_max_f32_e32 v229, v64, v64
	v_fmamk_f32 v64, v64, 0x3e0293ee, v230
	v_max_f32_e32 v228, v229, v228
	v_exp_f32_e32 v64, v64
	s_waitcnt lgkmcnt(6)
	v_mfma_f32_32x32x16_bf16 v[32:47], v[176:179], v[184:187], v[32:47]
	ds_read_b64_tr_b16 v[184:185], v158 offset:0x1200
	ds_read_b64_tr_b16 v[186:187], v158 offset:0x1a00
	v_fmamk_f32 v65, v65, 0x3e0293ee, v230
	v_max3_f32 v228, v228, v66, v67
	v_exp_f32_e32 v65, v65
	v_fmamk_f32 v66, v66, 0x3e0293ee, v230
	v_cvt_pk_bf16_f32 v112, v64, v65
	v_exp_f32_e32 v66, v66
	s_waitcnt lgkmcnt(6)
	v_mfma_f32_32x32x16_bf16 v[16:31], v[176:179], v[188:191], v[16:31]
	ds_read_b64_tr_b16 v[188:189], v158 offset:0x1400
	ds_read_b64_tr_b16 v[190:191], v158 offset:0x1c00
	v_fmamk_f32 v67, v67, 0x3e0293ee, v230
	v_max3_f32 v228, v228, v68, v69
	v_exp_f32_e32 v67, v67
	v_fmamk_f32 v68, v68, 0x3e0293ee, v230
	v_cvt_pk_bf16_f32 v113, v66, v67
	v_add_f32_e32 v231, 0, v64
	s_waitcnt lgkmcnt(6)
	v_mfma_f32_32x32x16_bf16 v[0:15], v[176:179], v[192:195], v[0:15]
	ds_read_b64_tr_b16 v[192:193], v158 offset:0x1600
	ds_read_b64_tr_b16 v[194:195], v158 offset:0x1e00
	v_exp_f32_e32 v68, v68
	v_fmamk_f32 v69, v69, 0x3e0293ee, v230
	v_max3_f32 v228, v228, v70, v71
	v_add_f32_e32 v231, v65, v231
	v_exp_f32_e32 v69, v69
	v_fmamk_f32 v70, v70, 0x3e0293ee, v230
	s_waitcnt lgkmcnt(6)
	v_mfma_f32_32x32x16_bf16 v[48:63], v[124:127], v[180:183], v[48:63]
	ds_read_b64_tr_b16 v[180:181], v158 offset:0x2000
	ds_read_b64_tr_b16 v[182:183], v158 offset:0x2800
	v_cvt_pk_bf16_f32 v114, v68, v69
	v_add_f32_e32 v231, v66, v231
	v_exp_f32_e32 v70, v70
	v_fmamk_f32 v71, v71, 0x3e0293ee, v230
	v_max3_f32 v228, v228, v72, v73
	v_add_f32_e32 v231, v67, v231
	s_waitcnt lgkmcnt(6)
	v_mfma_f32_32x32x16_bf16 v[32:47], v[124:127], v[184:187], v[32:47]
	ds_read_b64_tr_b16 v[184:185], v158 offset:0x2200
	ds_read_b64_tr_b16 v[186:187], v158 offset:0x2a00
	v_exp_f32_e32 v71, v71
	v_fmamk_f32 v72, v72, 0x3e0293ee, v230
	v_cvt_pk_bf16_f32 v115, v70, v71
	s_nop 1
	v_permlane32_swap_b32_e32 v112, v114
	v_permlane32_swap_b32_e32 v113, v115
	ds_write_b128 v157, v[112:115] offset:4096
	s_waitcnt lgkmcnt(7)
	v_mfma_f32_32x32x16_bf16 v[16:31], v[124:127], v[188:191], v[16:31]
	ds_read_b64_tr_b16 v[188:189], v158 offset:0x2400
	ds_read_b64_tr_b16 v[190:191], v158 offset:0x2c00
	v_add_f32_e32 v231, v68, v231
	v_exp_f32_e32 v72, v72
	v_fmamk_f32 v73, v73, 0x3e0293ee, v230
	v_max3_f32 v228, v228, v74, v75
	v_add_f32_e32 v231, v69, v231
	v_exp_f32_e32 v73, v73
	s_waitcnt lgkmcnt(7)
	v_mfma_f32_32x32x16_bf16 v[0:15], v[124:127], v[192:195], v[0:15]
	ds_read_b64_tr_b16 v[192:193], v158 offset:0x2600
	ds_read_b64_tr_b16 v[194:195], v158 offset:0x2e00
	v_fmamk_f32 v74, v74, 0x3e0293ee, v230
	v_cvt_pk_bf16_f32 v116, v72, v73
	v_add_f32_e32 v231, v70, v231
	v_exp_f32_e32 v74, v74
	v_fmamk_f32 v75, v75, 0x3e0293ee, v230
	v_max3_f32 v228, v228, v76, v77
	s_waitcnt lgkmcnt(7)
	v_mfma_f32_32x32x16_bf16 v[48:63], v[172:175], v[180:183], v[48:63]
	ds_read_b64_tr_b16 v[180:181], v158 offset:0x3000
	ds_read_b64_tr_b16 v[182:183], v158 offset:0x3800
	v_add_f32_e32 v231, v71, v231
	v_exp_f32_e32 v75, v75
	v_fmamk_f32 v76, v76, 0x3e0293ee, v230
	v_cvt_pk_bf16_f32 v117, v74, v75
	v_add_f32_e32 v231, v72, v231
	v_exp_f32_e32 v76, v76
	s_waitcnt lgkmcnt(7)
	v_mfma_f32_32x32x16_bf16 v[32:47], v[172:175], v[184:187], v[32:47]
	ds_read_b64_tr_b16 v[184:185], v158 offset:0x3200
	ds_read_b64_tr_b16 v[186:187], v158 offset:0x3a00
	v_fmamk_f32 v77, v77, 0x3e0293ee, v230
	v_max3_f32 v228, v228, v78, v79
	v_add_f32_e32 v231, v73, v231
	v_exp_f32_e32 v77, v77
	v_fmamk_f32 v78, v78, 0x3e0293ee, v230
	v_cvt_pk_bf16_f32 v118, v76, v77
	s_waitcnt lgkmcnt(6)
	v_mfma_f32_32x32x16_bf16 v[16:31], v[172:175], v[188:191], v[16:31]
	ds_read_b64_tr_b16 v[188:189], v158 offset:0x3400
	ds_read_b64_tr_b16 v[190:191], v158 offset:0x3c00
	v_add_f32_e32 v231, v74, v231
	v_exp_f32_e32 v78, v78
	v_fmac_f32_e32 v230, 0x3e0293ee, v79
	v_add_f32_e32 v231, v75, v231
	v_exp_f32_e32 v79, v230
	v_add_f32_e32 v230, v76, v231
	s_waitcnt lgkmcnt(6)
	v_mfma_f32_32x32x16_bf16 v[0:15], v[172:175], v[192:195], v[0:15]
	ds_read_b64_tr_b16 v[192:193], v158 offset:0x3600
	ds_read_b64_tr_b16 v[194:195], v158 offset:0x3e00
	v_cvt_pk_bf16_f32 v119, v78, v79
	s_nop 1
	v_permlane32_swap_b32_e32 v116, v118
	v_permlane32_swap_b32_e32 v117, v119
	ds_write_b128 v157, v[116:119] offset:5120
	v_mov_b32_e32 v229, v228
	v_add_f32_e32 v230, v77, v230
	s_waitcnt lgkmcnt(7)
	v_mfma_f32_32x32x16_bf16 v[48:63], v[168:171], v[180:183], v[48:63]
	s_nop 0
	v_permlane32_swap_b32_e32 v228, v229
	v_add_f32_e32 v230, v78, v230
	v_add_f32_e32 v120, v79, v230
	v_max_f32_e32 v229, v229, v229
	v_max_f32_e32 v228, v228, v228
	v_max_f32_e32 v164, v228, v229
	s_waitcnt lgkmcnt(5)
	v_mfma_f32_32x32x16_bf16 v[32:47], v[168:171], v[184:187], v[32:47]
	v_mov_b32_e32 v121, v120
	s_nop 1
	v_permlane32_swap_b32_e32 v120, v121
	v_add_f32_e32 v120, v120, v121
	v_add_f32_e32 v155, v155, v120
	s_waitcnt lgkmcnt(3)
	v_mfma_f32_32x32x16_bf16 v[16:31], v[168:171], v[188:191], v[16:31]
	s_waitcnt lgkmcnt(1)
	v_mfma_f32_32x32x16_bf16 v[0:15], v[168:171], v[192:195], v[0:15]
	s_and_saveexec_b64 s[52:53], s[4:5]
	ds_write_b32 v160, v164 offset:8448
	s_or_b64 exec, exec, s[52:53]
	s_waitcnt vmcnt(0)
	s_waitcnt vmcnt(0) lgkmcnt(0)
	s_barrier
	s_branch .LBB0_748

.Li1_sm:
	ds_read_b64_tr_b16 v[188:189], v158 offset:0x8400
	ds_read_b64_tr_b16 v[190:191], v158 offset:0x8c00
	ds_read_b64_tr_b16 v[192:193], v158 offset:0x8600
	ds_read_b64_tr_b16 v[194:195], v158 offset:0x8e00
	s_waitcnt lgkmcnt(6)
	v_mfma_f32_32x32x16_bf16 v[48:63], v[176:179], v[180:183], v[48:63]
	ds_read_b64_tr_b16 v[180:181], v158 offset:0x9000
	ds_read_b64_tr_b16 v[182:183], v158 offset:0x9800
	v_mul_f32_e32 v230, 0xbe0293ee, v165
	v_max_f32_e32 v228, v65, v65
	v_max_f32_e32 v229, v64, v64
	v_fmamk_f32 v64, v64, 0x3e0293ee, v230
	v_max_f32_e32 v228, v229, v228
	v_exp_f32_e32 v64, v64
	s_waitcnt lgkmcnt(6)
	v_mfma_f32_32x32x16_bf16 v[32:47], v[176:179], v[184:187], v[32:47]
	ds_read_b64_tr_b16 v[184:185], v158 offset:0x9200
	ds_read_b64_tr_b16 v[186:187], v158 offset:0x9a00
	v_fmamk_f32 v65, v65, 0x3e0293ee, v230
	v_max3_f32 v228, v228, v66, v67
	v_exp_f32_e32 v65, v65
	v_fmamk_f32 v66, v66, 0x3e0293ee, v230
	v_cvt_pk_bf16_f32 v112, v64, v65
	v_exp_f32_e32 v66, v66
	s_waitcnt lgkmcnt(6)
	v_mfma_f32_32x32x16_bf16 v[16:31], v[176:179], v[188:191], v[16:31]
	ds_read_b64_tr_b16 v[188:189], v158 offset:0x9400
	ds_read_b64_tr_b16 v[190:191], v158 offset:0x9c00
	v_fmamk_f32 v67, v67, 0x3e0293ee, v230
	v_max3_f32 v228, v228, v68, v69
	v_exp_f32_e32 v67, v67
	v_fmamk_f32 v68, v68, 0x3e0293ee, v230
	v_cvt_pk_bf16_f32 v113, v66, v67
	v_add_f32_e32 v231, 0, v64
	s_waitcnt lgkmcnt(6)
	v_mfma_f32_32x32x16_bf16 v[0:15], v[176:179], v[192:195], v[0:15]
	ds_read_b64_tr_b16 v[192:193], v158 offset:0x9600
	ds_read_b64_tr_b16 v[194:195], v158 offset:0x9e00
	v_exp_f32_e32 v68, v68
	v_fmamk_f32 v69, v69, 0x3e0293ee, v230
	v_max3_f32 v228, v228, v70, v71
	v_add_f32_e32 v231, v65, v231
	v_exp_f32_e32 v69, v69
	v_fmamk_f32 v70, v70, 0x3e0293ee, v230
	s_waitcnt lgkmcnt(6)
	v_mfma_f32_32x32x16_bf16 v[48:63], v[168:171], v[180:183], v[48:63]
	ds_read_b64_tr_b16 v[180:181], v158 offset:0xa000
	ds_read_b64_tr_b16 v[182:183], v158 offset:0xa800
	v_cvt_pk_bf16_f32 v114, v68, v69
	v_add_f32_e32 v231, v66, v231
	v_exp_f32_e32 v70, v70
	v_fmamk_f32 v71, v71, 0x3e0293ee, v230
	v_max3_f32 v228, v228, v72, v73
	v_add_f32_e32 v231, v67, v231
	s_waitcnt lgkmcnt(6)
	v_mfma_f32_32x32x16_bf16 v[32:47], v[168:171], v[184:187], v[32:47]
	ds_read_b64_tr_b16 v[184:185], v158 offset:0xa200
	ds_read_b64_tr_b16 v[186:187], v158 offset:0xaa00
	v_exp_f32_e32 v71, v71
	v_fmamk_f32 v72, v72, 0x3e0293ee, v230
	v_cvt_pk_bf16_f32 v115, v70, v71
	s_nop 1
	v_permlane32_swap_b32_e32 v112, v114
	v_permlane32_swap_b32_e32 v113, v115
	ds_write_b128 v157, v[112:115]
	s_waitcnt lgkmcnt(7)
	v_mfma_f32_32x32x16_bf16 v[16:31], v[168:171], v[188:191], v[16:31]
	ds_read_b64_tr_b16 v[188:189], v158 offset:0xa400
	ds_read_b64_tr_b16 v[190:191], v158 offset:0xac00
	v_add_f32_e32 v231, v68, v231
	v_exp_f32_e32 v72, v72
	v_fmamk_f32 v73, v73, 0x3e0293ee, v230
	v_max3_f32 v228, v228, v74, v75
	v_add_f32_e32 v231, v69, v231
	v_exp_f32_e32 v73, v73
	s_waitcnt lgkmcnt(7)
	v_mfma_f32_32x32x16_bf16 v[0:15], v[168:171], v[192:195], v[0:15]
	ds_read_b64_tr_b16 v[192:193], v158 offset:0xa600
	ds_read_b64_tr_b16 v[194:195], v158 offset:0xae00
	v_fmamk_f32 v74, v74, 0x3e0293ee, v230
	v_cvt_pk_bf16_f32 v116, v72, v73
	v_add_f32_e32 v231, v70, v231
	v_exp_f32_e32 v74, v74
	v_fmamk_f32 v75, v75, 0x3e0293ee, v230
	v_max3_f32 v228, v228, v76, v77
	s_waitcnt lgkmcnt(7)
	v_mfma_f32_32x32x16_bf16 v[48:63], v[172:175], v[180:183], v[48:63]
	ds_read_b64_tr_b16 v[180:181], v158 offset:0xb000
	ds_read_b64_tr_b16 v[182:183], v158 offset:0xb800
	v_add_f32_e32 v231, v71, v231
	v_exp_f32_e32 v75, v75
	v_fmamk_f32 v76, v76, 0x3e0293ee, v230
	v_cvt_pk_bf16_f32 v117, v74, v75
	v_add_f32_e32 v231, v72, v231
	v_exp_f32_e32 v76, v76
	s_waitcnt lgkmcnt(7)
	v_mfma_f32_32x32x16_bf16 v[32:47], v[172:175], v[184:187], v[32:47]
	ds_read_b64_tr_b16 v[184:185], v158 offset:0xb200
	ds_read_b64_tr_b16 v[186:187], v158 offset:0xba00
	v_fmamk_f32 v77, v77, 0x3e0293ee, v230
	v_max3_f32 v228, v228, v78, v79
	v_add_f32_e32 v231, v73, v231
	v_exp_f32_e32 v77, v77
	v_fmamk_f32 v78, v78, 0x3e0293ee, v230
	v_cvt_pk_bf16_f32 v118, v76, v77
	s_waitcnt lgkmcnt(6)
	v_mfma_f32_32x32x16_bf16 v[16:31], v[172:175], v[188:191], v[16:31]
	ds_read_b64_tr_b16 v[188:189], v158 offset:0xb400
	ds_read_b64_tr_b16 v[190:191], v158 offset:0xbc00
	v_add_f32_e32 v231, v74, v231
	v_exp_f32_e32 v78, v78
	v_fmac_f32_e32 v230, 0x3e0293ee, v79
	v_add_f32_e32 v231, v75, v231
	v_exp_f32_e32 v79, v230
	v_add_f32_e32 v230, v76, v231
	s_waitcnt lgkmcnt(6)
	v_mfma_f32_32x32x16_bf16 v[0:15], v[172:175], v[192:195], v[0:15]
	ds_read_b64_tr_b16 v[192:193], v158 offset:0xb600
	ds_read_b64_tr_b16 v[194:195], v158 offset:0xbe00
	v_cvt_pk_bf16_f32 v119, v78, v79
	s_nop 1
	v_permlane32_swap_b32_e32 v116, v118
	v_permlane32_swap_b32_e32 v117, v119
	ds_write_b128 v157, v[116:119] offset:1024
	v_mov_b32_e32 v229, v228
	v_add_f32_e32 v230, v77, v230
	s_waitcnt lgkmcnt(7)
	v_mfma_f32_32x32x16_bf16 v[48:63], v[124:127], v[180:183], v[48:63]
	s_nop 0
	v_permlane32_swap_b32_e32 v228, v229
	v_add_f32_e32 v230, v78, v230
	v_add_f32_e32 v120, v79, v230
	v_max_f32_e32 v229, v229, v229
	v_max_f32_e32 v228, v228, v228
	v_max_f32_e32 v164, v228, v229
	s_waitcnt lgkmcnt(5)
	v_mfma_f32_32x32x16_bf16 v[32:47], v[124:127], v[184:187], v[32:47]
	v_mov_b32_e32 v121, v120
	s_nop 1
	v_permlane32_swap_b32_e32 v120, v121
	v_add_f32_e32 v120, v120, v121
	v_add_f32_e32 v155, v155, v120
	s_waitcnt lgkmcnt(3)
	v_mfma_f32_32x32x16_bf16 v[16:31], v[124:127], v[188:191], v[16:31]
	s_waitcnt lgkmcnt(1)
	v_mfma_f32_32x32x16_bf16 v[0:15], v[124:127], v[192:195], v[0:15]
	s_and_saveexec_b64 s[54:55], s[4:5]
	ds_write_b32 v160, v164 offset:8192
	s_or_b64 exec, exec, s[54:55]
	s_waitcnt vmcnt(0)
	s_waitcnt vmcnt(0) lgkmcnt(0)
	s_barrier
	s_branch .LBB0_733
